# v070 + attention PV sections with counted lgkmcnt waits (each V fragment pair waited four MFMAs after its issue)
# speedup vs baseline: 1.0055x; 1.0021x over previous
.LBB0_563:
	ds_read_b64_tr_b16 v[208:209], v176 offset:0
	ds_read_b64_tr_b16 v[210:211], v176 offset:0x800
	ds_read_b64_tr_b16 v[222:223], v176 offset:0x1000
	ds_read_b64_tr_b16 v[224:225], v176 offset:0x1800
	ds_read_b64_tr_b16 v[226:227], v176 offset:0x2000
	ds_read_b64_tr_b16 v[228:229], v176 offset:0x2800
	ds_read_b64_tr_b16 v[230:231], v176 offset:0x3000
	ds_read_b64_tr_b16 v[232:233], v176 offset:0x3800
	s_nop 0
	s_waitcnt lgkmcnt(6)
	v_mfma_f32_32x32x16_bf16 v[50:65], v[98:101], v[208:211], v[50:65]
	ds_read_b64_tr_b16 v[208:209], v176 offset:0x200
	ds_read_b64_tr_b16 v[210:211], v176 offset:0xa00
	s_waitcnt lgkmcnt(6)
	v_mfma_f32_32x32x16_bf16 v[50:65], v[102:105], v[222:225], v[50:65]
	ds_read_b64_tr_b16 v[222:223], v176 offset:0x1200
	ds_read_b64_tr_b16 v[224:225], v176 offset:0x1a00
	s_waitcnt lgkmcnt(6)
	v_mfma_f32_32x32x16_bf16 v[50:65], v[106:109], v[226:229], v[50:65]
	ds_read_b64_tr_b16 v[226:227], v176 offset:0x2200
	ds_read_b64_tr_b16 v[228:229], v176 offset:0x2a00
	s_waitcnt lgkmcnt(6)
	v_mfma_f32_32x32x16_bf16 v[50:65], v[110:113], v[230:233], v[50:65]
	ds_read_b64_tr_b16 v[230:231], v176 offset:0x3200
	ds_read_b64_tr_b16 v[232:233], v176 offset:0x3a00
	s_waitcnt lgkmcnt(6)
	v_mfma_f32_32x32x16_bf16 v[34:49], v[98:101], v[208:211], v[34:49]
	ds_read_b64_tr_b16 v[208:209], v176 offset:0x400
	ds_read_b64_tr_b16 v[210:211], v176 offset:0xc00
	s_waitcnt lgkmcnt(6)
	v_mfma_f32_32x32x16_bf16 v[34:49], v[102:105], v[222:225], v[34:49]
	ds_read_b64_tr_b16 v[222:223], v176 offset:0x1400
	ds_read_b64_tr_b16 v[224:225], v176 offset:0x1c00
	s_waitcnt lgkmcnt(6)
	v_mfma_f32_32x32x16_bf16 v[34:49], v[106:109], v[226:229], v[34:49]
	ds_read_b64_tr_b16 v[226:227], v176 offset:0x2400
	ds_read_b64_tr_b16 v[228:229], v176 offset:0x2c00
	s_waitcnt lgkmcnt(6)
	v_mfma_f32_32x32x16_bf16 v[34:49], v[110:113], v[230:233], v[34:49]
	ds_read_b64_tr_b16 v[230:231], v176 offset:0x3400
	ds_read_b64_tr_b16 v[232:233], v176 offset:0x3c00
	s_waitcnt lgkmcnt(6)
	v_mfma_f32_32x32x16_bf16 v[18:33], v[98:101], v[208:211], v[18:33]
	ds_read_b64_tr_b16 v[208:209], v176 offset:0x600
	ds_read_b64_tr_b16 v[210:211], v176 offset:0xe00
	s_waitcnt lgkmcnt(6)
	v_mfma_f32_32x32x16_bf16 v[18:33], v[102:105], v[222:225], v[18:33]
	ds_read_b64_tr_b16 v[222:223], v176 offset:0x1600
	ds_read_b64_tr_b16 v[224:225], v176 offset:0x1e00
	s_waitcnt lgkmcnt(6)
	v_mfma_f32_32x32x16_bf16 v[18:33], v[106:109], v[226:229], v[18:33]
	ds_read_b64_tr_b16 v[226:227], v176 offset:0x2600
	ds_read_b64_tr_b16 v[228:229], v176 offset:0x2e00
	s_waitcnt lgkmcnt(6)
	v_mfma_f32_32x32x16_bf16 v[18:33], v[110:113], v[230:233], v[18:33]
	ds_read_b64_tr_b16 v[230:231], v176 offset:0x3600
	ds_read_b64_tr_b16 v[232:233], v176 offset:0x3e00
	s_waitcnt lgkmcnt(6)
	v_mfma_f32_32x32x16_bf16 v[2:17], v[98:101], v[208:211], v[2:17]
	v_max_f32_e32 v98, v83, v83
	v_max_f32_e32 v99, v82, v82
	v_max_f32_e32 v98, v99, v98
	v_max3_f32 v98, v98, v84, v85
	v_max3_f32 v98, v98, v86, v87
	v_max3_f32 v98, v98, v88, v89
	v_max3_f32 v98, v98, v90, v91
	v_max3_f32 v98, v98, v92, v93
	v_max3_f32 v98, v98, v94, v95
	s_waitcnt lgkmcnt(4)
	v_mfma_f32_32x32x16_bf16 v[2:17], v[102:105], v[222:225], v[2:17]
	v_max3_f32 v98, v98, v96, v97
	v_max3_f32 v98, v98, v66, v67
	v_max3_f32 v98, v98, v68, v69
	v_max3_f32 v98, v98, v70, v71
	v_max3_f32 v98, v98, v72, v73
	v_max3_f32 v98, v98, v74, v75
	v_max3_f32 v98, v98, v76, v77
	v_max3_f32 v98, v98, v78, v79
	s_waitcnt lgkmcnt(2)
	v_mfma_f32_32x32x16_bf16 v[2:17], v[106:109], v[226:229], v[2:17]
	v_max3_f32 v98, v98, v80, v81
	v_mov_b32_e32 v99, v98
	s_nop 1
	v_permlane32_swap_b32_e32 v98, v99
	v_max_f32_e32 v99, v99, v99
	v_max_f32_e32 v98, v98, v98
	v_max_f32_e32 v98, v98, v99
	v_sub_f32_e32 v99, v98, v193
	v_cmp_ge_f32_e32 vcc, s91, v99
	v_max_f32_e32 v99, v193, v193
	v_max_f32_e32 v209, v99, v98
	s_waitcnt lgkmcnt(0)
	v_mfma_f32_32x32x16_bf16 v[2:17], v[110:113], v[230:233], v[2:17]
	v_sub_f32_e32 v98, v193, v209
	v_mul_f32_e32 v98, 0x3e0293ee, v98
	v_exp_f32_e32 v98, v98
	s_cmp_eq_u64 vcc, exec
	s_waitcnt lgkmcnt(0)
	s_waitcnt vmcnt(0)
	s_barrier
	s_cselect_b64 s[38:39], -1, 0
	s_waitcnt vmcnt(0)
	v_cndmask_b32_e64 v208, v98, 1.0, s[38:39]
	v_cmp_gt_f32_e32 vcc, 1.0, v208
	s_lshl_b32 s42, s21, 11
	s_mov_b32 m0, s42
	s_nop 0
	global_load_lds_dwordx4 v128, s[98:99]
	s_add_i32 m0, s42, 0x400
	s_nop 0
	global_load_lds_dwordx4 v129, s[98:99]
	s_cbranch_vccz .LBB0_571
	s_and_saveexec_b64 s[42:43], s[0:1]
	ds_write_b32 v177, v208 offset:128
	s_or_b64 exec, exec, s[42:43]
	s_waitcnt lgkmcnt(0)
	v_add_u32_e32 v110, s70, v164
	ds_read_b128 v[98:101], v110 offset:224
	ds_read_b128 v[102:105], v110 offset:192
	ds_read_b128 v[106:109], v110 offset:160
	ds_read_b128 v[110:113], v110 offset:128
	s_waitcnt lgkmcnt(3)
	v_pk_mul_f32 v[62:63], v[62:63], v[98:99]
	s_waitcnt lgkmcnt(2)
	v_pk_mul_f32 v[58:59], v[58:59], v[102:103]
	s_waitcnt lgkmcnt(1)
	v_pk_mul_f32 v[54:55], v[54:55], v[106:107]
	v_pk_mul_f32 v[64:65], v[64:65], v[100:101]
	v_pk_mul_f32 v[60:61], v[60:61], v[104:105]
	v_pk_mul_f32 v[56:57], v[56:57], v[108:109]
	s_waitcnt lgkmcnt(0)
	v_pk_mul_f32 v[52:53], v[52:53], v[112:113]
	v_pk_mul_f32 v[50:51], v[50:51], v[110:111]
	v_pk_mul_f32 v[46:47], v[46:47], v[98:99]
	v_pk_mul_f32 v[42:43], v[42:43], v[102:103]
	v_pk_mul_f32 v[38:39], v[38:39], v[106:107]
	v_pk_mul_f32 v[48:49], v[48:49], v[100:101]
	v_pk_mul_f32 v[44:45], v[44:45], v[104:105]
	v_pk_mul_f32 v[40:41], v[40:41], v[108:109]
	v_pk_mul_f32 v[36:37], v[36:37], v[112:113]
	v_pk_mul_f32 v[34:35], v[34:35], v[110:111]
	v_pk_mul_f32 v[30:31], v[30:31], v[98:99]
	v_pk_mul_f32 v[26:27], v[26:27], v[102:103]
	v_pk_mul_f32 v[22:23], v[22:23], v[106:107]
	v_pk_mul_f32 v[32:33], v[32:33], v[100:101]
	v_pk_mul_f32 v[28:29], v[28:29], v[104:105]
	v_pk_mul_f32 v[24:25], v[24:25], v[108:109]
	v_pk_mul_f32 v[20:21], v[20:21], v[112:113]
	v_pk_mul_f32 v[18:19], v[18:19], v[110:111]
	v_pk_mul_f32 v[14:15], v[14:15], v[98:99]
	v_pk_mul_f32 v[10:11], v[10:11], v[102:103]
	v_pk_mul_f32 v[6:7], v[6:7], v[106:107]
	v_pk_mul_f32 v[16:17], v[16:17], v[100:101]
	v_pk_mul_f32 v[12:13], v[12:13], v[104:105]
	v_pk_mul_f32 v[8:9], v[8:9], v[108:109]
	v_pk_mul_f32 v[4:5], v[4:5], v[112:113]
	v_pk_mul_f32 v[2:3], v[2:3], v[110:111]

.LBB0_574:
	ds_read_b64_tr_b16 v[222:223], v195 offset:0
	ds_read_b64_tr_b16 v[224:225], v195 offset:0x800
	ds_read_b64_tr_b16 v[226:227], v195 offset:0x1000
	ds_read_b64_tr_b16 v[228:229], v195 offset:0x1800
	ds_read_b64_tr_b16 v[230:231], v195 offset:0x2000
	ds_read_b64_tr_b16 v[232:233], v195 offset:0x2800
	ds_read_b64_tr_b16 v[234:235], v195 offset:0x3000
	ds_read_b64_tr_b16 v[236:237], v195 offset:0x3800
	s_nop 0
	s_waitcnt lgkmcnt(6)
	v_mfma_f32_32x32x16_bf16 v[50:65], v[66:69], v[222:225], v[50:65]
	ds_read_b64_tr_b16 v[222:223], v195 offset:0x200
	ds_read_b64_tr_b16 v[224:225], v195 offset:0xa00
	s_waitcnt lgkmcnt(6)
	v_mfma_f32_32x32x16_bf16 v[50:65], v[70:73], v[226:229], v[50:65]
	ds_read_b64_tr_b16 v[226:227], v195 offset:0x1200
	ds_read_b64_tr_b16 v[228:229], v195 offset:0x1a00
	s_waitcnt lgkmcnt(6)
	v_mfma_f32_32x32x16_bf16 v[50:65], v[90:93], v[230:233], v[50:65]
	ds_read_b64_tr_b16 v[230:231], v195 offset:0x2200
	ds_read_b64_tr_b16 v[232:233], v195 offset:0x2a00
	s_waitcnt lgkmcnt(6)
	v_mfma_f32_32x32x16_bf16 v[50:65], v[94:97], v[234:237], v[50:65]
	ds_read_b64_tr_b16 v[234:235], v195 offset:0x3200
	ds_read_b64_tr_b16 v[236:237], v195 offset:0x3a00
	s_waitcnt lgkmcnt(6)
	v_mfma_f32_32x32x16_bf16 v[34:49], v[66:69], v[222:225], v[34:49]
	ds_read_b64_tr_b16 v[222:223], v195 offset:0x400
	ds_read_b64_tr_b16 v[224:225], v195 offset:0xc00
	s_waitcnt lgkmcnt(6)
	v_mfma_f32_32x32x16_bf16 v[34:49], v[70:73], v[226:229], v[34:49]
	ds_read_b64_tr_b16 v[226:227], v195 offset:0x1400
	ds_read_b64_tr_b16 v[228:229], v195 offset:0x1c00
	s_waitcnt lgkmcnt(6)
	v_mfma_f32_32x32x16_bf16 v[34:49], v[90:93], v[230:233], v[34:49]
	ds_read_b64_tr_b16 v[230:231], v195 offset:0x2400
	ds_read_b64_tr_b16 v[232:233], v195 offset:0x2c00
	s_waitcnt lgkmcnt(6)
	v_mfma_f32_32x32x16_bf16 v[34:49], v[94:97], v[234:237], v[34:49]
	ds_read_b64_tr_b16 v[234:235], v195 offset:0x3400
	ds_read_b64_tr_b16 v[236:237], v195 offset:0x3c00
	s_waitcnt lgkmcnt(6)
	v_mfma_f32_32x32x16_bf16 v[18:33], v[66:69], v[222:225], v[18:33]
	ds_read_b64_tr_b16 v[222:223], v195 offset:0x600
	ds_read_b64_tr_b16 v[224:225], v195 offset:0xe00
	s_waitcnt lgkmcnt(6)
	v_mfma_f32_32x32x16_bf16 v[18:33], v[70:73], v[226:229], v[18:33]
	ds_read_b64_tr_b16 v[226:227], v195 offset:0x1600
	ds_read_b64_tr_b16 v[228:229], v195 offset:0x1e00
	s_waitcnt lgkmcnt(6)
	v_mfma_f32_32x32x16_bf16 v[18:33], v[90:93], v[230:233], v[18:33]
	ds_read_b64_tr_b16 v[230:231], v195 offset:0x2600
	ds_read_b64_tr_b16 v[232:233], v195 offset:0x2e00
	s_waitcnt lgkmcnt(6)
	v_mfma_f32_32x32x16_bf16 v[18:33], v[94:97], v[234:237], v[18:33]
	ds_read_b64_tr_b16 v[234:235], v195 offset:0x3600
	ds_read_b64_tr_b16 v[236:237], v195 offset:0x3e00
	s_waitcnt lgkmcnt(6)
	v_mfma_f32_32x32x16_bf16 v[2:17], v[66:69], v[222:225], v[2:17]
	v_max_f32_e32 v66, v115, v115
	v_max_f32_e32 v67, v114, v114
	v_max_f32_e32 v66, v67, v66
	v_max3_f32 v66, v66, v116, v117
	v_max3_f32 v66, v66, v118, v119
	v_max3_f32 v66, v66, v120, v121
	v_max3_f32 v66, v66, v122, v123
	v_max3_f32 v66, v66, v124, v125
	v_max3_f32 v66, v66, v126, v127
	s_waitcnt lgkmcnt(4)
	v_mfma_f32_32x32x16_bf16 v[2:17], v[70:73], v[226:229], v[2:17]
	v_max3_f32 v66, v66, v128, v129
	v_max3_f32 v66, v66, v98, v99
	v_max3_f32 v66, v66, v100, v101
	v_max3_f32 v66, v66, v102, v103
	v_max3_f32 v66, v66, v104, v105
	v_max3_f32 v66, v66, v106, v107
	v_max3_f32 v66, v66, v108, v109
	v_max3_f32 v66, v66, v110, v111
	s_waitcnt lgkmcnt(2)
	v_mfma_f32_32x32x16_bf16 v[2:17], v[90:93], v[230:233], v[2:17]
	v_max3_f32 v66, v66, v112, v113
	v_mov_b32_e32 v67, v66
	s_nop 1
	v_permlane32_swap_b32_e32 v66, v67
	v_max_f32_e32 v67, v67, v67
	v_max_f32_e32 v66, v66, v66
	v_max_f32_e32 v66, v66, v67
	v_sub_f32_e32 v67, v66, v193
	v_cmp_ge_f32_e32 vcc, s91, v67
	v_max_f32_e32 v67, v193, v193
	v_max_f32_e32 v66, v67, v66
	s_waitcnt lgkmcnt(0)
	v_mfma_f32_32x32x16_bf16 v[2:17], v[94:97], v[234:237], v[2:17]
	v_sub_f32_e32 v67, v193, v66
	v_mul_f32_e32 v67, 0x3e0293ee, v67
	v_exp_f32_e32 v67, v67
	s_cmp_eq_u64 vcc, exec
	s_waitcnt lgkmcnt(0)
	s_waitcnt vmcnt(0)
	s_barrier
	s_cselect_b64 s[38:39], -1, 0
	s_waitcnt vmcnt(0)
	v_cndmask_b32_e64 v197, v67, 1.0, s[38:39]
	v_cmp_gt_f32_e32 vcc, 1.0, v197
	s_lshl_b32 s42, s21, 11
	s_add_i32 m0, s42, 0x4000
	s_nop 0
	global_load_lds_dwordx4 v88, s[100:101]
	s_add_i32 m0, s42, 0x4400
	s_nop 0
	global_load_lds_dwordx4 v89, s[100:101]
	s_cbranch_vccz .LBB0_582
	s_and_saveexec_b64 s[40:41], s[0:1]
	ds_write_b32 v177, v197 offset:128
	s_or_b64 exec, exec, s[40:41]
	s_waitcnt lgkmcnt(0)
	v_add_u32_e32 v67, s70, v164
	ds_read_b128 v[68:71], v67 offset:224
	ds_read_b128 v[72:75], v67 offset:192
	ds_read_b128 v[76:79], v67 offset:128
	ds_read_b128 v[80:83], v67 offset:160
	s_waitcnt lgkmcnt(3)
	v_pk_mul_f32 v[64:65], v[64:65], v[70:71]
	v_pk_mul_f32 v[62:63], v[62:63], v[68:69]
	s_waitcnt lgkmcnt(2)
	v_pk_mul_f32 v[60:61], v[60:61], v[74:75]
	v_pk_mul_f32 v[58:59], v[58:59], v[72:73]
	s_waitcnt lgkmcnt(0)
	v_pk_mul_f32 v[56:57], v[56:57], v[82:83]
	v_pk_mul_f32 v[54:55], v[54:55], v[80:81]
	v_pk_mul_f32 v[52:53], v[52:53], v[78:79]
	v_pk_mul_f32 v[50:51], v[50:51], v[76:77]
	v_pk_mul_f32 v[48:49], v[48:49], v[70:71]
	v_pk_mul_f32 v[46:47], v[46:47], v[68:69]
	v_pk_mul_f32 v[44:45], v[44:45], v[74:75]
	v_pk_mul_f32 v[42:43], v[42:43], v[72:73]
	v_pk_mul_f32 v[40:41], v[40:41], v[82:83]
	v_pk_mul_f32 v[38:39], v[38:39], v[80:81]
	v_pk_mul_f32 v[36:37], v[36:37], v[78:79]
	v_pk_mul_f32 v[34:35], v[34:35], v[76:77]
	v_pk_mul_f32 v[32:33], v[32:33], v[70:71]
	v_pk_mul_f32 v[30:31], v[30:31], v[68:69]
	v_pk_mul_f32 v[28:29], v[28:29], v[74:75]
	v_pk_mul_f32 v[26:27], v[26:27], v[72:73]
	v_pk_mul_f32 v[24:25], v[24:25], v[82:83]
	v_pk_mul_f32 v[22:23], v[22:23], v[80:81]
	v_pk_mul_f32 v[20:21], v[20:21], v[78:79]
	v_pk_mul_f32 v[18:19], v[18:19], v[76:77]
	v_pk_mul_f32 v[16:17], v[16:17], v[70:71]
	v_pk_mul_f32 v[14:15], v[14:15], v[68:69]
	v_pk_mul_f32 v[12:13], v[12:13], v[74:75]
	v_pk_mul_f32 v[10:11], v[10:11], v[72:73]
	v_pk_mul_f32 v[8:9], v[8:9], v[82:83]
	v_pk_mul_f32 v[6:7], v[6:7], v[80:81]
	v_pk_mul_f32 v[4:5], v[4:5], v[78:79]
	v_pk_mul_f32 v[2:3], v[2:3], v[76:77]
